# SwiGLU epilogue: rstd folded into the exponent scale and the reciprocal (g u / ((1 + 2^(-log2e rs g)) x), x = mean-square + eps): 4 packed f32 ops per pair instead of 6, all f32
# baseline (speedup 1.0000x reference)
; __device__ __forceinline__ void rows_rstd(const float* part, int M, int row0, int fr, int fq, float (&rs)[8]) {
;     const int L = fr | (fq << 4); const float* p = part + (row0 - fr) + L; float sa = 0.f, sb = 0.f;
; #pragma unroll
;     for (int i = 0; i < 32; ++i) { sa += p[(size_t)i * M]; sb += p[(size_t)i * M + HALF]; }
;     const int ra = __builtin_bit_cast(int, rsqrtf(sa * (1.0f / 2048.0f) + RMS_EPS)), rb = __builtin_bit_cast(int, rsqrtf(sb * (1.0f / 2048.0f) + RMS_EPS));
;     __device__ __forceinline__ void operator()(const f32x4 (&acc)[2][2][4][2], const Unit& u, int wr, int wc, int fr, int fq) const {
;         const int row0 = u.pm * BM + wr * 64 + fr; const int col0 = u.pn * HALF + wc * 32 + 8 * fq;
;         float rs8[8]; rows_rstd(part, M, row0, fr, fq, rs8);
.LBB0_931:
	s_lshl_b32 s0, s35, 8
	s_add_i32 s0, s0, s53
	v_or_b32_e32 v150, s0, v145
	v_mul_lo_u32 v150, v150, s82
	v_lshl_or_b32 v143, s34, 7, v166
	v_lshl_add_u32 v150, v143, 1, v150
	v_and_b32_e32 v148, 0x60, v166
	v_lshlrev_b32_e32 v148, 5, v148
	s_lshl_b32 s1, s53, 6
	s_add_i32 s1, s1, 0x21000
	v_add_u32_e32 v146, s1, v148
	v_lshl_add_u32 v148, v145, 2, v146
	s_cmp_eq_u32 s100, s35
	s_cbranch_scc1 .Lepi_g3_cached
	v_readfirstlane_b32 s98, v134
	v_readfirstlane_b32 s99, v135
	v_lshlrev_b32_e32 v142, 2, v145
	v_and_b32_e32 v143, 0x18, v166
	v_lshl_add_u32 v142, v143, 3, v142
	v_add_u32_e32 v146, v146, v142
	s_lshl_b32 s0, s0, 2
	v_add_u32_e32 v142, s0, v142
	s_nop 1
	global_load_dword v168, v142, s[98:99]
	global_load_dword v169, v142, s[98:99] offset:512
	s_add_u32 s98, s98, 0x20000
	s_addc_u32 s99, s99, 0
	global_load_dword v170, v142, s[98:99]
	global_load_dword v171, v142, s[98:99] offset:512
	s_add_u32 s98, s98, 0x20000
	s_addc_u32 s99, s99, 0
	global_load_dword v172, v142, s[98:99]
	global_load_dword v173, v142, s[98:99] offset:512
	s_add_u32 s98, s98, 0x20000
	s_addc_u32 s99, s99, 0
	global_load_dword v174, v142, s[98:99]
	global_load_dword v175, v142, s[98:99] offset:512
	s_add_u32 s98, s98, 0x20000
	s_addc_u32 s99, s99, 0
	global_load_dword v176, v142, s[98:99]
	global_load_dword v177, v142, s[98:99] offset:512
	s_add_u32 s98, s98, 0x20000
	s_addc_u32 s99, s99, 0
	global_load_dword v178, v142, s[98:99]
	global_load_dword v179, v142, s[98:99] offset:512
	s_add_u32 s98, s98, 0x20000
	s_addc_u32 s99, s99, 0
	global_load_dword v180, v142, s[98:99]
	global_load_dword v181, v142, s[98:99] offset:512
	s_add_u32 s98, s98, 0x20000
	s_addc_u32 s99, s99, 0
	global_load_dword v182, v142, s[98:99]
	global_load_dword v183, v142, s[98:99] offset:512
	s_add_u32 s98, s98, 0x20000
	s_addc_u32 s99, s99, 0
	global_load_dword v184, v142, s[98:99]
	global_load_dword v185, v142, s[98:99] offset:512
	s_add_u32 s98, s98, 0x20000
	s_addc_u32 s99, s99, 0
	global_load_dword v186, v142, s[98:99]
	global_load_dword v187, v142, s[98:99] offset:512
	s_add_u32 s98, s98, 0x20000
	s_addc_u32 s99, s99, 0
	global_load_dword v188, v142, s[98:99]
	global_load_dword v189, v142, s[98:99] offset:512
	s_add_u32 s98, s98, 0x20000
	s_addc_u32 s99, s99, 0
	global_load_dword v190, v142, s[98:99]
	global_load_dword v191, v142, s[98:99] offset:512
	s_add_u32 s98, s98, 0x20000
	s_addc_u32 s99, s99, 0
	global_load_dword v192, v142, s[98:99]
	global_load_dword v193, v142, s[98:99] offset:512
	s_add_u32 s98, s98, 0x20000
	s_addc_u32 s99, s99, 0
	global_load_dword v194, v142, s[98:99]
	global_load_dword v195, v142, s[98:99] offset:512
	s_add_u32 s98, s98, 0x20000
	s_addc_u32 s99, s99, 0
	global_load_dword v196, v142, s[98:99]
	global_load_dword v197, v142, s[98:99] offset:512
	s_add_u32 s98, s98, 0x20000
	s_addc_u32 s99, s99, 0
	global_load_dword v198, v142, s[98:99]
	global_load_dword v199, v142, s[98:99] offset:512
	s_add_u32 s98, s98, 0x20000
	s_addc_u32 s99, s99, 0
	global_load_dword v200, v142, s[98:99]
	global_load_dword v201, v142, s[98:99] offset:512
	s_add_u32 s98, s98, 0x20000
	s_addc_u32 s99, s99, 0
	global_load_dword v202, v142, s[98:99]
	global_load_dword v203, v142, s[98:99] offset:512
	s_add_u32 s98, s98, 0x20000
	s_addc_u32 s99, s99, 0
	global_load_dword v204, v142, s[98:99]
	global_load_dword v205, v142, s[98:99] offset:512
	s_add_u32 s98, s98, 0x20000
	s_addc_u32 s99, s99, 0
	global_load_dword v206, v142, s[98:99]
	global_load_dword v207, v142, s[98:99] offset:512
	s_add_u32 s98, s98, 0x20000
	s_addc_u32 s99, s99, 0
	global_load_dword v208, v142, s[98:99]
	global_load_dword v209, v142, s[98:99] offset:512
	s_add_u32 s98, s98, 0x20000
	s_addc_u32 s99, s99, 0
	global_load_dword v210, v142, s[98:99]
	global_load_dword v211, v142, s[98:99] offset:512
	s_add_u32 s98, s98, 0x20000
	s_addc_u32 s99, s99, 0
	global_load_dword v212, v142, s[98:99]
	global_load_dword v213, v142, s[98:99] offset:512
	s_add_u32 s98, s98, 0x20000
	s_addc_u32 s99, s99, 0
	global_load_dword v214, v142, s[98:99]
	global_load_dword v215, v142, s[98:99] offset:512
	s_add_u32 s98, s98, 0x20000
	s_addc_u32 s99, s99, 0
	global_load_dword v216, v142, s[98:99]
	global_load_dword v217, v142, s[98:99] offset:512
	s_add_u32 s98, s98, 0x20000
	s_addc_u32 s99, s99, 0
	global_load_dword v218, v142, s[98:99]
	global_load_dword v219, v142, s[98:99] offset:512
	s_add_u32 s98, s98, 0x20000
	s_addc_u32 s99, s99, 0
	global_load_dword v220, v142, s[98:99]
	global_load_dword v221, v142, s[98:99] offset:512
	s_add_u32 s98, s98, 0x20000
	s_addc_u32 s99, s99, 0
	global_load_dword v222, v142, s[98:99]
	global_load_dword v223, v142, s[98:99] offset:512
	s_add_u32 s98, s98, 0x20000
	s_addc_u32 s99, s99, 0
	global_load_dword v224, v142, s[98:99]
	global_load_dword v225, v142, s[98:99] offset:512
	s_add_u32 s98, s98, 0x20000
	s_addc_u32 s99, s99, 0
	global_load_dword v226, v142, s[98:99]
	global_load_dword v227, v142, s[98:99] offset:512
	s_add_u32 s98, s98, 0x20000
	s_addc_u32 s99, s99, 0
	global_load_dword v228, v142, s[98:99]
	global_load_dword v229, v142, s[98:99] offset:512
	s_add_u32 s98, s98, 0x20000
	s_addc_u32 s99, s99, 0
	global_load_dword v140, v142, s[98:99]
	global_load_dword v141, v142, s[98:99] offset:512
	s_waitcnt vmcnt(62)
	v_add_f32_e32 v143, 0, v168
	v_add_f32_e32 v144, 0, v169
	s_waitcnt vmcnt(60)
	v_add_f32_e32 v143, v143, v170
	v_add_f32_e32 v144, v144, v171
	s_waitcnt vmcnt(58)
	v_add_f32_e32 v143, v143, v172
	v_add_f32_e32 v144, v144, v173
	s_waitcnt vmcnt(56)
	v_add_f32_e32 v143, v143, v174
	v_add_f32_e32 v144, v144, v175
	s_waitcnt vmcnt(54)
	v_add_f32_e32 v143, v143, v176
	v_add_f32_e32 v144, v144, v177
	s_waitcnt vmcnt(52)
; __device__ __forceinline__ unsigned cvt_pk_bf16(float lo, float hi) { unsigned r; asm volatile("s_nop 0\n\tv_cvt_pk_bf16_f32 %0, %1, %2" : "=v"(r) : "v"(lo), "v"(hi)); return r; }
; __device__ __forceinline__ float silu_mul(float g, float u) { return g * u * __builtin_amdgcn_rcpf(1.0f + __expf(-g)); }
; __device__ __forceinline__ void rows_rstd(const float* part, int M, int row0, int fr, int fq, float (&rs)[8]) {
;     ...
;     for (int i = 0; i < 32; ++i) { sa += p[(size_t)i * M]; sb += p[(size_t)i * M + HALF]; }
;     const int ra = __builtin_bit_cast(int, rsqrtf(sa * (1.0f / 2048.0f) + RMS_EPS)), rb = __builtin_bit_cast(int, rsqrtf(sb * (1.0f / 2048.0f) + RMS_EPS));
; #pragma unroll
;     for (int r = 0; r < 8; ++r) rs[r] = __builtin_bit_cast(float, __builtin_amdgcn_ds_bpermute(((r & 3) * 16 + fr) << 2, (r >> 2) ? rb : ra));
;     __device__ __forceinline__ void operator()(const f32x4 (&acc)[2][2][4][2], const Unit& u, int wr, int wc, int fr, int fq) const {
;     ...
;             for (int m = 0; m < 4; ++m) { const int row = row0 + ai * HALF + m * 16; const float rs = rs8[ai * 4 + m];
;                 const f32x4 g0 = acc[ai][0][m][0] * rs, g1 = acc[ai][0][m][1] * rs, u0 = acc[ai][1][m][0] * rs, u1 = acc[ai][1][m][1] * rs;
;                 u32x4 w; w.x = cvt_pk_bf16(silu_mul(g0[0], u0[0]), silu_mul(g0[1], u0[1])); w.y = cvt_pk_bf16(silu_mul(g0[2], u0[2]), silu_mul(g0[3], u0[3]));
;                 w.z = cvt_pk_bf16(silu_mul(g1[0], u1[0]), silu_mul(g1[1], u1[1])); w.w = cvt_pk_bf16(silu_mul(g1[2], u1[2]), silu_mul(g1[3], u1[3]));
;                 *(u32x4*)(H + (size_t)row * ldh + col0) = w; }
	v_add_f32_e32 v143, v143, v178
	v_add_f32_e32 v144, v144, v179
	s_waitcnt vmcnt(50)
	v_add_f32_e32 v143, v143, v180
	v_add_f32_e32 v144, v144, v181
	s_waitcnt vmcnt(48)
	v_add_f32_e32 v143, v143, v182
	v_add_f32_e32 v144, v144, v183
	s_waitcnt vmcnt(46)
	v_add_f32_e32 v143, v143, v184
	v_add_f32_e32 v144, v144, v185
	s_waitcnt vmcnt(44)
	v_add_f32_e32 v143, v143, v186
	v_add_f32_e32 v144, v144, v187
	s_waitcnt vmcnt(42)
	v_add_f32_e32 v143, v143, v188
	v_add_f32_e32 v144, v144, v189
	s_waitcnt vmcnt(40)
	v_add_f32_e32 v143, v143, v190
	v_add_f32_e32 v144, v144, v191
	s_waitcnt vmcnt(38)
	v_add_f32_e32 v143, v143, v192
	v_add_f32_e32 v144, v144, v193
	s_waitcnt vmcnt(36)
	v_add_f32_e32 v143, v143, v194
	v_add_f32_e32 v144, v144, v195
	s_waitcnt vmcnt(34)
	v_add_f32_e32 v143, v143, v196
	v_add_f32_e32 v144, v144, v197
	s_waitcnt vmcnt(32)
	v_add_f32_e32 v143, v143, v198
	v_add_f32_e32 v144, v144, v199
	s_waitcnt vmcnt(30)
	v_add_f32_e32 v143, v143, v200
	v_add_f32_e32 v144, v144, v201
	s_waitcnt vmcnt(28)
	v_add_f32_e32 v143, v143, v202
	v_add_f32_e32 v144, v144, v203
	s_waitcnt vmcnt(26)
	v_add_f32_e32 v143, v143, v204
	v_add_f32_e32 v144, v144, v205
	s_waitcnt vmcnt(24)
	v_add_f32_e32 v143, v143, v206
	v_add_f32_e32 v144, v144, v207
	s_waitcnt vmcnt(22)
	v_add_f32_e32 v143, v143, v208
	v_add_f32_e32 v144, v144, v209
	s_waitcnt vmcnt(20)
	v_add_f32_e32 v143, v143, v210
	v_add_f32_e32 v144, v144, v211
	s_waitcnt vmcnt(18)
	v_add_f32_e32 v143, v143, v212
	v_add_f32_e32 v144, v144, v213
	s_waitcnt vmcnt(16)
	v_add_f32_e32 v143, v143, v214
	v_add_f32_e32 v144, v144, v215
	s_waitcnt vmcnt(14)
	v_add_f32_e32 v143, v143, v216
	v_add_f32_e32 v144, v144, v217
	s_waitcnt vmcnt(12)
	v_add_f32_e32 v143, v143, v218
	v_add_f32_e32 v144, v144, v219
	s_waitcnt vmcnt(10)
	v_add_f32_e32 v143, v143, v220
	v_add_f32_e32 v144, v144, v221
	s_waitcnt vmcnt(8)
	v_add_f32_e32 v143, v143, v222
	v_add_f32_e32 v144, v144, v223
	s_waitcnt vmcnt(6)
	v_add_f32_e32 v143, v143, v224
	v_add_f32_e32 v144, v144, v225
	s_waitcnt vmcnt(4)
	v_add_f32_e32 v143, v143, v226
	v_add_f32_e32 v144, v144, v227
	s_waitcnt vmcnt(2)
	v_add_f32_e32 v143, v143, v228
	v_add_f32_e32 v144, v144, v229
	s_waitcnt vmcnt(0)
	v_add_f32_e32 v143, v143, v140
	v_add_f32_e32 v144, v144, v141
	s_mov_b32 s1, 0x3a000000
	v_fma_f32 v143, v143, s1, v158
	v_fma_f32 v144, v144, s1, v158
	v_rsq_f32_e32 v140, v143
	v_rsq_f32_e32 v141, v144
	s_mov_b32 s100, s35
	ds_write_b32 v146, v143 offset:512
	ds_write_b32 v146, v144 offset:768
	ds_write_b32 v146, v140
	ds_write_b32 v146, v141 offset:256
.Lepi_g3_cached:
	ds_read_b32 v168, v148 offset:0
	ds_read_b32 v200, v148 offset:512
	ds_read_b32 v170, v148 offset:64
	ds_read_b32 v202, v148 offset:576
	ds_read_b32 v172, v148 offset:128
	ds_read_b32 v204, v148 offset:640
	ds_read_b32 v174, v148 offset:192
	ds_read_b32 v206, v148 offset:704
	ds_read_b32 v176, v148 offset:256
	ds_read_b32 v208, v148 offset:768
	ds_read_b32 v178, v148 offset:320
	ds_read_b32 v210, v148 offset:832
	ds_read_b32 v180, v148 offset:384
	ds_read_b32 v212, v148 offset:896
	ds_read_b32 v182, v148 offset:448
	ds_read_b32 v214, v148 offset:960
	s_lshl_b32 s0, s82, 4
	s_mul_i32 s1, s82, 0x50
	v_mov_b32_e32 v142, 0xbfb8aa3b
	s_waitcnt lgkmcnt(14)
	v_mul_f32_e32 v168, 0xbfb8aa3b, v168
	v_pk_mul_f32 v[184:185], v[124:125], v[168:169] op_sel_hi:[1,0]
	v_pk_mul_f32 v[186:187], v[126:127], v[168:169] op_sel_hi:[1,0]
	v_pk_mul_f32 v[188:189], v[120:121], v[168:169] op_sel_hi:[1,0]
	v_pk_mul_f32 v[190:191], v[122:123], v[168:169] op_sel_hi:[1,0]
	v_pk_mul_f32 v[116:117], v[124:125], v[116:117]
	v_pk_mul_f32 v[118:119], v[126:127], v[118:119]
	v_pk_mul_f32 v[112:113], v[120:121], v[112:113]
	v_pk_mul_f32 v[114:115], v[122:123], v[114:115]
	v_exp_f32_e32 v184, v184
	v_exp_f32_e32 v185, v185
	v_exp_f32_e32 v186, v186
	v_exp_f32_e32 v187, v187
	v_exp_f32_e32 v188, v188
	v_exp_f32_e32 v189, v189
	v_exp_f32_e32 v190, v190
	v_exp_f32_e32 v191, v191
	v_pk_fma_f32 v[184:185], v[184:185], v[200:201], v[200:201] op_sel_hi:[1,0,0]
	v_pk_fma_f32 v[186:187], v[186:187], v[200:201], v[200:201] op_sel_hi:[1,0,0]
	v_pk_fma_f32 v[188:189], v[188:189], v[200:201], v[200:201] op_sel_hi:[1,0,0]
	v_pk_fma_f32 v[190:191], v[190:191], v[200:201], v[200:201] op_sel_hi:[1,0,0]
	v_rcp_f32_e32 v184, v184
	v_rcp_f32_e32 v185, v185
	v_rcp_f32_e32 v186, v186
	v_rcp_f32_e32 v187, v187
	v_rcp_f32_e32 v188, v188
	v_rcp_f32_e32 v189, v189
	v_rcp_f32_e32 v190, v190
	v_rcp_f32_e32 v191, v191
	v_pk_mul_f32 v[116:117], v[116:117], v[184:185]
	v_pk_mul_f32 v[118:119], v[118:119], v[186:187]
	v_pk_mul_f32 v[112:113], v[112:113], v[188:189]
	v_pk_mul_f32 v[114:115], v[114:115], v[190:191]
	v_cvt_pk_bf16_f32 v192, v116, v117
	v_cvt_pk_bf16_f32 v193, v118, v119
	v_cvt_pk_bf16_f32 v194, v112, v113
	v_cvt_pk_bf16_f32 v195, v114, v115
	global_store_dwordx4 v150, v[192:195], s[16:17]
	v_add_u32_e32 v150, s0, v150
	s_waitcnt lgkmcnt(12)
; __device__ __forceinline__ unsigned cvt_pk_bf16(float lo, float hi) { unsigned r; asm volatile("s_nop 0\n\tv_cvt_pk_bf16_f32 %0, %1, %2" : "=v"(r) : "v"(lo), "v"(hi)); return r; }
; __device__ __forceinline__ float silu_mul(float g, float u) { return g * u * __builtin_amdgcn_rcpf(1.0f + __expf(-g)); }
;     __device__ __forceinline__ void operator()(const f32x4 (&acc)[2][2][4][2], const Unit& u, int wr, int wc, int fr, int fq) const {
;     ...
;             for (int m = 0; m < 4; ++m) { const int row = row0 + ai * HALF + m * 16; const float rs = rs8[ai * 4 + m];
;                 const f32x4 g0 = acc[ai][0][m][0] * rs, g1 = acc[ai][0][m][1] * rs, u0 = acc[ai][1][m][0] * rs, u1 = acc[ai][1][m][1] * rs;
;                 u32x4 w; w.x = cvt_pk_bf16(silu_mul(g0[0], u0[0]), silu_mul(g0[1], u0[1])); w.y = cvt_pk_bf16(silu_mul(g0[2], u0[2]), silu_mul(g0[3], u0[3]));
;                 w.z = cvt_pk_bf16(silu_mul(g1[0], u1[0]), silu_mul(g1[1], u1[1])); w.w = cvt_pk_bf16(silu_mul(g1[2], u1[2]), silu_mul(g1[3], u1[3]));
;                 *(u32x4*)(H + (size_t)row * ldh + col0) = w; }
	v_mul_f32_e32 v170, 0xbfb8aa3b, v170
	v_pk_mul_f32 v[184:185], v[108:109], v[170:171] op_sel_hi:[1,0]
	v_pk_mul_f32 v[186:187], v[110:111], v[170:171] op_sel_hi:[1,0]
	v_pk_mul_f32 v[188:189], v[104:105], v[170:171] op_sel_hi:[1,0]
	v_pk_mul_f32 v[190:191], v[106:107], v[170:171] op_sel_hi:[1,0]
	v_pk_mul_f32 v[100:101], v[108:109], v[100:101]
	v_pk_mul_f32 v[102:103], v[110:111], v[102:103]
	v_pk_mul_f32 v[96:97], v[104:105], v[96:97]
	v_pk_mul_f32 v[98:99], v[106:107], v[98:99]
	v_exp_f32_e32 v184, v184
	v_exp_f32_e32 v185, v185
	v_exp_f32_e32 v186, v186
	v_exp_f32_e32 v187, v187
	v_exp_f32_e32 v188, v188
	v_exp_f32_e32 v189, v189
	v_exp_f32_e32 v190, v190
	v_exp_f32_e32 v191, v191
	v_pk_fma_f32 v[184:185], v[184:185], v[202:203], v[202:203] op_sel_hi:[1,0,0]
	v_pk_fma_f32 v[186:187], v[186:187], v[202:203], v[202:203] op_sel_hi:[1,0,0]
	v_pk_fma_f32 v[188:189], v[188:189], v[202:203], v[202:203] op_sel_hi:[1,0,0]
	v_pk_fma_f32 v[190:191], v[190:191], v[202:203], v[202:203] op_sel_hi:[1,0,0]
	v_rcp_f32_e32 v184, v184
	v_rcp_f32_e32 v185, v185
	v_rcp_f32_e32 v186, v186
	v_rcp_f32_e32 v187, v187
	v_rcp_f32_e32 v188, v188
	v_rcp_f32_e32 v189, v189
	v_rcp_f32_e32 v190, v190
	v_rcp_f32_e32 v191, v191
	v_pk_mul_f32 v[100:101], v[100:101], v[184:185]
	v_pk_mul_f32 v[102:103], v[102:103], v[186:187]
	v_pk_mul_f32 v[96:97], v[96:97], v[188:189]
	v_pk_mul_f32 v[98:99], v[98:99], v[190:191]
	v_cvt_pk_bf16_f32 v196, v100, v101
	v_cvt_pk_bf16_f32 v197, v102, v103
	v_cvt_pk_bf16_f32 v198, v96, v97
	v_cvt_pk_bf16_f32 v199, v98, v99
	global_store_dwordx4 v150, v[196:199], s[16:17]
	v_add_u32_e32 v150, s0, v150
	s_waitcnt lgkmcnt(10)
	v_mul_f32_e32 v172, 0xbfb8aa3b, v172
	v_pk_mul_f32 v[184:185], v[92:93], v[172:173] op_sel_hi:[1,0]
	v_pk_mul_f32 v[186:187], v[94:95], v[172:173] op_sel_hi:[1,0]
	v_pk_mul_f32 v[188:189], v[88:89], v[172:173] op_sel_hi:[1,0]
	v_pk_mul_f32 v[190:191], v[90:91], v[172:173] op_sel_hi:[1,0]
	v_pk_mul_f32 v[84:85], v[92:93], v[84:85]
	v_pk_mul_f32 v[86:87], v[94:95], v[86:87]
	v_pk_mul_f32 v[80:81], v[88:89], v[80:81]
	v_pk_mul_f32 v[82:83], v[90:91], v[82:83]
	v_exp_f32_e32 v184, v184
	v_exp_f32_e32 v185, v185
	v_exp_f32_e32 v186, v186
	v_exp_f32_e32 v187, v187
	v_exp_f32_e32 v188, v188
	v_exp_f32_e32 v189, v189
	v_exp_f32_e32 v190, v190
	v_exp_f32_e32 v191, v191
	v_pk_fma_f32 v[184:185], v[184:185], v[204:205], v[204:205] op_sel_hi:[1,0,0]
	v_pk_fma_f32 v[186:187], v[186:187], v[204:205], v[204:205] op_sel_hi:[1,0,0]
	v_pk_fma_f32 v[188:189], v[188:189], v[204:205], v[204:205] op_sel_hi:[1,0,0]
	v_pk_fma_f32 v[190:191], v[190:191], v[204:205], v[204:205] op_sel_hi:[1,0,0]
	v_rcp_f32_e32 v184, v184
	v_rcp_f32_e32 v185, v185
	v_rcp_f32_e32 v186, v186
	v_rcp_f32_e32 v187, v187
	v_rcp_f32_e32 v188, v188
	v_rcp_f32_e32 v189, v189
	v_rcp_f32_e32 v190, v190
	v_rcp_f32_e32 v191, v191
	v_pk_mul_f32 v[84:85], v[84:85], v[184:185]
	v_pk_mul_f32 v[86:87], v[86:87], v[186:187]
	v_pk_mul_f32 v[80:81], v[80:81], v[188:189]
	v_pk_mul_f32 v[82:83], v[82:83], v[190:191]
	v_cvt_pk_bf16_f32 v192, v84, v85
	v_cvt_pk_bf16_f32 v193, v86, v87
	v_cvt_pk_bf16_f32 v194, v80, v81
	v_cvt_pk_bf16_f32 v195, v82, v83
	global_store_dwordx4 v150, v[192:195], s[16:17]
	v_add_u32_e32 v150, s0, v150
	s_waitcnt lgkmcnt(8)
	v_mul_f32_e32 v174, 0xbfb8aa3b, v174
	v_pk_mul_f32 v[184:185], v[76:77], v[174:175] op_sel_hi:[1,0]
	v_pk_mul_f32 v[186:187], v[78:79], v[174:175] op_sel_hi:[1,0]
	v_pk_mul_f32 v[188:189], v[72:73], v[174:175] op_sel_hi:[1,0]
	v_pk_mul_f32 v[190:191], v[74:75], v[174:175] op_sel_hi:[1,0]
	v_pk_mul_f32 v[68:69], v[76:77], v[68:69]
	v_pk_mul_f32 v[70:71], v[78:79], v[70:71]
	v_pk_mul_f32 v[64:65], v[72:73], v[64:65]
	v_pk_mul_f32 v[66:67], v[74:75], v[66:67]
	v_exp_f32_e32 v184, v184
	v_exp_f32_e32 v185, v185
	v_exp_f32_e32 v186, v186
	v_exp_f32_e32 v187, v187
	v_exp_f32_e32 v188, v188
	v_exp_f32_e32 v189, v189
	v_exp_f32_e32 v190, v190
	v_exp_f32_e32 v191, v191
	v_pk_fma_f32 v[184:185], v[184:185], v[206:207], v[206:207] op_sel_hi:[1,0,0]
	v_pk_fma_f32 v[186:187], v[186:187], v[206:207], v[206:207] op_sel_hi:[1,0,0]
	v_pk_fma_f32 v[188:189], v[188:189], v[206:207], v[206:207] op_sel_hi:[1,0,0]
	v_pk_fma_f32 v[190:191], v[190:191], v[206:207], v[206:207] op_sel_hi:[1,0,0]
	v_rcp_f32_e32 v184, v184
	v_rcp_f32_e32 v185, v185
	v_rcp_f32_e32 v186, v186
	v_rcp_f32_e32 v187, v187
	v_rcp_f32_e32 v188, v188
	v_rcp_f32_e32 v189, v189
	v_rcp_f32_e32 v190, v190
	v_rcp_f32_e32 v191, v191
	v_pk_mul_f32 v[68:69], v[68:69], v[184:185]
	v_pk_mul_f32 v[70:71], v[70:71], v[186:187]
	v_pk_mul_f32 v[64:65], v[64:65], v[188:189]
	v_pk_mul_f32 v[66:67], v[66:67], v[190:191]
	v_cvt_pk_bf16_f32 v196, v68, v69
	v_cvt_pk_bf16_f32 v197, v70, v71
	v_cvt_pk_bf16_f32 v198, v64, v65
	v_cvt_pk_bf16_f32 v199, v66, v67
	global_store_dwordx4 v150, v[196:199], s[16:17]
	v_add_u32_e32 v150, s1, v150
	s_waitcnt lgkmcnt(6)
; __device__ __forceinline__ unsigned cvt_pk_bf16(float lo, float hi) { unsigned r; asm volatile("s_nop 0\n\tv_cvt_pk_bf16_f32 %0, %1, %2" : "=v"(r) : "v"(lo), "v"(hi)); return r; }
; __device__ __forceinline__ float silu_mul(float g, float u) { return g * u * __builtin_amdgcn_rcpf(1.0f + __expf(-g)); }
;     __device__ __forceinline__ void operator()(const f32x4 (&acc)[2][2][4][2], const Unit& u, int wr, int wc, int fr, int fq) const {
;     ...
;             for (int m = 0; m < 4; ++m) { const int row = row0 + ai * HALF + m * 16; const float rs = rs8[ai * 4 + m];
;                 const f32x4 g0 = acc[ai][0][m][0] * rs, g1 = acc[ai][0][m][1] * rs, u0 = acc[ai][1][m][0] * rs, u1 = acc[ai][1][m][1] * rs;
;                 u32x4 w; w.x = cvt_pk_bf16(silu_mul(g0[0], u0[0]), silu_mul(g0[1], u0[1])); w.y = cvt_pk_bf16(silu_mul(g0[2], u0[2]), silu_mul(g0[3], u0[3]));
;                 w.z = cvt_pk_bf16(silu_mul(g1[0], u1[0]), silu_mul(g1[1], u1[1])); w.w = cvt_pk_bf16(silu_mul(g1[2], u1[2]), silu_mul(g1[3], u1[3]));
;                 *(u32x4*)(H + (size_t)row * ldh + col0) = w; }
	v_mul_f32_e32 v176, 0xbfb8aa3b, v176
	v_pk_mul_f32 v[184:185], v[60:61], v[176:177] op_sel_hi:[1,0]
	v_pk_mul_f32 v[186:187], v[62:63], v[176:177] op_sel_hi:[1,0]
	v_pk_mul_f32 v[188:189], v[56:57], v[176:177] op_sel_hi:[1,0]
	v_pk_mul_f32 v[190:191], v[58:59], v[176:177] op_sel_hi:[1,0]
	v_pk_mul_f32 v[52:53], v[60:61], v[52:53]
	v_pk_mul_f32 v[54:55], v[62:63], v[54:55]
	v_pk_mul_f32 v[48:49], v[56:57], v[48:49]
	v_pk_mul_f32 v[50:51], v[58:59], v[50:51]
	v_exp_f32_e32 v184, v184
	v_exp_f32_e32 v185, v185
	v_exp_f32_e32 v186, v186
	v_exp_f32_e32 v187, v187
	v_exp_f32_e32 v188, v188
	v_exp_f32_e32 v189, v189
	v_exp_f32_e32 v190, v190
	v_exp_f32_e32 v191, v191
	v_pk_fma_f32 v[184:185], v[184:185], v[208:209], v[208:209] op_sel_hi:[1,0,0]
	v_pk_fma_f32 v[186:187], v[186:187], v[208:209], v[208:209] op_sel_hi:[1,0,0]
	v_pk_fma_f32 v[188:189], v[188:189], v[208:209], v[208:209] op_sel_hi:[1,0,0]
	v_pk_fma_f32 v[190:191], v[190:191], v[208:209], v[208:209] op_sel_hi:[1,0,0]
	v_rcp_f32_e32 v184, v184
	v_rcp_f32_e32 v185, v185
	v_rcp_f32_e32 v186, v186
	v_rcp_f32_e32 v187, v187
	v_rcp_f32_e32 v188, v188
	v_rcp_f32_e32 v189, v189
	v_rcp_f32_e32 v190, v190
	v_rcp_f32_e32 v191, v191
	v_pk_mul_f32 v[52:53], v[52:53], v[184:185]
	v_pk_mul_f32 v[54:55], v[54:55], v[186:187]
	v_pk_mul_f32 v[48:49], v[48:49], v[188:189]
	v_pk_mul_f32 v[50:51], v[50:51], v[190:191]
	v_cvt_pk_bf16_f32 v192, v52, v53
	v_cvt_pk_bf16_f32 v193, v54, v55
	v_cvt_pk_bf16_f32 v194, v48, v49
	v_cvt_pk_bf16_f32 v195, v50, v51
	global_store_dwordx4 v150, v[192:195], s[16:17]
	v_add_u32_e32 v150, s0, v150
	s_waitcnt lgkmcnt(4)
	v_mul_f32_e32 v178, 0xbfb8aa3b, v178
	v_pk_mul_f32 v[184:185], v[44:45], v[178:179] op_sel_hi:[1,0]
	v_pk_mul_f32 v[186:187], v[46:47], v[178:179] op_sel_hi:[1,0]
	v_pk_mul_f32 v[188:189], v[40:41], v[178:179] op_sel_hi:[1,0]
	v_pk_mul_f32 v[190:191], v[42:43], v[178:179] op_sel_hi:[1,0]
	v_pk_mul_f32 v[36:37], v[44:45], v[36:37]
	v_pk_mul_f32 v[38:39], v[46:47], v[38:39]
	v_pk_mul_f32 v[32:33], v[40:41], v[32:33]
	v_pk_mul_f32 v[34:35], v[42:43], v[34:35]
	v_exp_f32_e32 v184, v184
	v_exp_f32_e32 v185, v185
	v_exp_f32_e32 v186, v186
	v_exp_f32_e32 v187, v187
	v_exp_f32_e32 v188, v188
	v_exp_f32_e32 v189, v189
	v_exp_f32_e32 v190, v190
	v_exp_f32_e32 v191, v191
	v_pk_fma_f32 v[184:185], v[184:185], v[210:211], v[210:211] op_sel_hi:[1,0,0]
	v_pk_fma_f32 v[186:187], v[186:187], v[210:211], v[210:211] op_sel_hi:[1,0,0]
	v_pk_fma_f32 v[188:189], v[188:189], v[210:211], v[210:211] op_sel_hi:[1,0,0]
	v_pk_fma_f32 v[190:191], v[190:191], v[210:211], v[210:211] op_sel_hi:[1,0,0]
	v_rcp_f32_e32 v184, v184
	v_rcp_f32_e32 v185, v185
	v_rcp_f32_e32 v186, v186
	v_rcp_f32_e32 v187, v187
	v_rcp_f32_e32 v188, v188
	v_rcp_f32_e32 v189, v189
	v_rcp_f32_e32 v190, v190
	v_rcp_f32_e32 v191, v191
	v_pk_mul_f32 v[36:37], v[36:37], v[184:185]
	v_pk_mul_f32 v[38:39], v[38:39], v[186:187]
	v_pk_mul_f32 v[32:33], v[32:33], v[188:189]
	v_pk_mul_f32 v[34:35], v[34:35], v[190:191]
	v_cvt_pk_bf16_f32 v196, v36, v37
	v_cvt_pk_bf16_f32 v197, v38, v39
	v_cvt_pk_bf16_f32 v198, v32, v33
	v_cvt_pk_bf16_f32 v199, v34, v35
	global_store_dwordx4 v150, v[196:199], s[16:17]
	v_add_u32_e32 v150, s0, v150
	s_waitcnt lgkmcnt(2)
	v_mul_f32_e32 v180, 0xbfb8aa3b, v180
	v_pk_mul_f32 v[184:185], v[28:29], v[180:181] op_sel_hi:[1,0]
	v_pk_mul_f32 v[186:187], v[30:31], v[180:181] op_sel_hi:[1,0]
	v_pk_mul_f32 v[188:189], v[24:25], v[180:181] op_sel_hi:[1,0]
	v_pk_mul_f32 v[190:191], v[26:27], v[180:181] op_sel_hi:[1,0]
	v_pk_mul_f32 v[20:21], v[28:29], v[20:21]
	v_pk_mul_f32 v[22:23], v[30:31], v[22:23]
	v_pk_mul_f32 v[16:17], v[24:25], v[16:17]
	v_pk_mul_f32 v[18:19], v[26:27], v[18:19]
	v_exp_f32_e32 v184, v184
	v_exp_f32_e32 v185, v185
	v_exp_f32_e32 v186, v186
	v_exp_f32_e32 v187, v187
	v_exp_f32_e32 v188, v188
	v_exp_f32_e32 v189, v189
	v_exp_f32_e32 v190, v190
	v_exp_f32_e32 v191, v191
	v_pk_fma_f32 v[184:185], v[184:185], v[212:213], v[212:213] op_sel_hi:[1,0,0]
	v_pk_fma_f32 v[186:187], v[186:187], v[212:213], v[212:213] op_sel_hi:[1,0,0]
	v_pk_fma_f32 v[188:189], v[188:189], v[212:213], v[212:213] op_sel_hi:[1,0,0]
	v_pk_fma_f32 v[190:191], v[190:191], v[212:213], v[212:213] op_sel_hi:[1,0,0]
	v_rcp_f32_e32 v184, v184
	v_rcp_f32_e32 v185, v185
	v_rcp_f32_e32 v186, v186
	v_rcp_f32_e32 v187, v187
	v_rcp_f32_e32 v188, v188
	v_rcp_f32_e32 v189, v189
	v_rcp_f32_e32 v190, v190
	v_rcp_f32_e32 v191, v191
	v_pk_mul_f32 v[20:21], v[20:21], v[184:185]
	v_pk_mul_f32 v[22:23], v[22:23], v[186:187]
	v_pk_mul_f32 v[16:17], v[16:17], v[188:189]
	v_pk_mul_f32 v[18:19], v[18:19], v[190:191]
	v_cvt_pk_bf16_f32 v192, v20, v21
	v_cvt_pk_bf16_f32 v193, v22, v23
	v_cvt_pk_bf16_f32 v194, v16, v17
	v_cvt_pk_bf16_f32 v195, v18, v19
	global_store_dwordx4 v150, v[192:195], s[16:17]
	v_add_u32_e32 v150, s0, v150
	s_waitcnt lgkmcnt(0)
	v_mul_f32_e32 v182, 0xbfb8aa3b, v182
	v_pk_mul_f32 v[184:185], v[12:13], v[182:183] op_sel_hi:[1,0]
	v_pk_mul_f32 v[186:187], v[14:15], v[182:183] op_sel_hi:[1,0]
	v_pk_mul_f32 v[188:189], v[8:9], v[182:183] op_sel_hi:[1,0]
	v_pk_mul_f32 v[190:191], v[10:11], v[182:183] op_sel_hi:[1,0]
	v_pk_mul_f32 v[4:5], v[12:13], v[4:5]
	v_pk_mul_f32 v[6:7], v[14:15], v[6:7]
	v_pk_mul_f32 v[0:1], v[8:9], v[0:1]
	v_pk_mul_f32 v[2:3], v[10:11], v[2:3]
	v_exp_f32_e32 v184, v184
	v_exp_f32_e32 v185, v185
	v_exp_f32_e32 v186, v186
	v_exp_f32_e32 v187, v187
	v_exp_f32_e32 v188, v188
	v_exp_f32_e32 v189, v189
	v_exp_f32_e32 v190, v190
	v_exp_f32_e32 v191, v191
	v_pk_fma_f32 v[184:185], v[184:185], v[214:215], v[214:215] op_sel_hi:[1,0,0]
	v_pk_fma_f32 v[186:187], v[186:187], v[214:215], v[214:215] op_sel_hi:[1,0,0]
	v_pk_fma_f32 v[188:189], v[188:189], v[214:215], v[214:215] op_sel_hi:[1,0,0]
	v_pk_fma_f32 v[190:191], v[190:191], v[214:215], v[214:215] op_sel_hi:[1,0,0]
	v_rcp_f32_e32 v184, v184
	v_rcp_f32_e32 v185, v185
	v_rcp_f32_e32 v186, v186
	v_rcp_f32_e32 v187, v187
	v_rcp_f32_e32 v188, v188
	v_rcp_f32_e32 v189, v189
	v_rcp_f32_e32 v190, v190
	v_rcp_f32_e32 v191, v191
	v_pk_mul_f32 v[4:5], v[4:5], v[184:185]
	v_pk_mul_f32 v[6:7], v[6:7], v[186:187]
	v_pk_mul_f32 v[0:1], v[0:1], v[188:189]
	v_pk_mul_f32 v[2:3], v[2:3], v[190:191]
	v_cvt_pk_bf16_f32 v196, v4, v5
	v_cvt_pk_bf16_f32 v197, v6, v7
	v_cvt_pk_bf16_f32 v198, v0, v1
	v_cvt_pk_bf16_f32 v199, v2, v3
	global_store_dwordx4 v150, v[196:199], s[16:17]
	s_and_b64 vcc, exec, s[4:5]
	s_mov_b64 s[0:1], -1
	s_cbranch_vccnz .LBB0_919
	s_andn2_b64 vcc, exec, s[14:15]
	s_cbranch_vccnz .LBB0_918
	s_barrier
	s_branch .LBB0_918
